# adds: scan stepper output-store address computed once per 4 steps with DS immediate offsets
# speedup vs baseline: 1.0037x; 1.0037x over previous
; __device__ __forceinline__ void scan_phase(LAS unsigned char* lds, const ScanArgs A) {
;     ...
;                 for (int t = 0; t < T; ++t) {
;                     const int tn = (t + 1 < T) ? (t + 1) : t;
;                     bf16x8 nA0, nA1; float nv; f32x2 nc12;
;                     SCAN_LDA(nA0, nA1, nv, nc12, tn);
;                     const f32x4 z4 = (f32x4){0.f, 0.f, 0.f, 0.f};
;                     const f32x4 d0 = __builtin_amdgcn_mfma_f32_16x16x32_bf16(cA0, sb0, z4, 0, 0, 0);
;                     const f32x4 d1 = __builtin_amdgcn_mfma_f32_16x16x32_bf16(cA1, sb1, z4, 0, 0, 0);
;                     f32x4 nw[4], na[4];
;                     SCAN_LDWA(nw, na, tn);
;                     const float sa = -(d0[0] + d1[0]);
;                     const float ov = (d0[1] + d1[1]) + sa * cc12.x + cv * cc12.y;
;                     const f32x2 sa2 = (f32x2){sa, sa}, v2 = (f32x2){cv, cv};
;                     f32x2 tq[2][4];
; #pragma unroll
;                     for (int hh = 0; hh < 2; ++hh) {
;                         tq[hh][0] = sa2 * (f32x2){ca[2 * hh][0], ca[2 * hh][1]}; tq[hh][1] = sa2 * (f32x2){ca[2 * hh][2], ca[2 * hh][3]};
;                         tq[hh][2] = sa2 * (f32x2){ca[2 * hh + 1][0], ca[2 * hh + 1][1]}; tq[hh][3] = sa2 * (f32x2){ca[2 * hh + 1][2], ca[2 * hh + 1][3]}; }
; #pragma unroll
;                     for (int hh = 0; hh < 2; ++hh) {
;                         tq[hh][0] = S[hh][0] * (f32x2){cw[2 * hh][0], cw[2 * hh][1]} + tq[hh][0]; tq[hh][1] = S[hh][1] * (f32x2){cw[2 * hh][2], cw[2 * hh][3]} + tq[hh][1];
;                         tq[hh][2] = S[hh][2] * (f32x2){cw[2 * hh + 1][0], cw[2 * hh + 1][1]} + tq[hh][2]; tq[hh][3] = S[hh][3] * (f32x2){cw[2 * hh + 1][2], cw[2 * hh + 1][3]} + tq[hh][3]; }
; #pragma unroll
;                     for (int hh = 0; hh < 2; ++hh) {
;                         S[hh][0] = v2 * (f32x2){cm[2 * hh][0], cm[2 * hh][1]} + tq[hh][0]; S[hh][1] = v2 * (f32x2){cm[2 * hh][2], cm[2 * hh][3]} + tq[hh][1];
;                         S[hh][2] = v2 * (f32x2){cm[2 * hh + 1][0], cm[2 * hh + 1][1]} + tq[hh][2]; S[hh][3] = v2 * (f32x2){cm[2 * hh + 1][2], cm[2 * hh + 1][3]} + tq[hh][3];
;                         const bf16x8 sbn = __builtin_bit_cast(bf16x8, (u32x4){cvt_pk_bf16(S[hh][0].x, S[hh][0].y), cvt_pk_bf16(S[hh][1].x, S[hh][1].y), cvt_pk_bf16(S[hh][2].x, S[hh][2].y), cvt_pk_bf16(S[hh][3].x, S[hh][3].y)});
.LBB0_1083:
	s_waitcnt lgkmcnt(14)
	v_mfma_f32_16x16x32_bf16 v[240:243], v[54:57], v[78:81], 0
	v_add_u32_e32 v230, v8, v218
	ds_read_b128 v[86:89], v230
	ds_read_b128 v[90:93], v230 offset:64
	v_add_u32_e32 v239, v8, v217
	v_mfma_f32_16x16x32_bf16 v[242:245], v[58:61], v[82:85], 0
	v_add_u32_e32 v229, v8, v202
	ds_read_b32 v179, v239
	ds_read_b64 v[180:181], v8 offset:3104
	ds_read_b128 v[82:85], v229 offset:1568
	ds_read_b128 v[78:81], v229 offset:1584
	ds_read_b128 v[58:61], v229 offset:1696
	ds_read_b128 v[54:57], v229 offset:1712
	ds_read_b128 v[106:109], v229 offset:1824
	ds_read_b128 v[102:105], v229 offset:1840
	ds_read_b128 v[98:101], v229 offset:1952
	ds_read_b128 v[94:97], v229 offset:1968
	v_add_f32_e32 v174, v240, v242
	s_waitcnt lgkmcnt(14)
	v_pk_mul_f32 v[176:177], v[174:175], v[176:177]
	v_pk_mul_f32 v[74:75], v[74:75], v[174:175] op_sel_hi:[1,0] neg_lo:[0,1] neg_hi:[0,1]
	v_pk_mul_f32 v[76:77], v[76:77], v[174:175] op_sel_hi:[1,0] neg_lo:[0,1] neg_hi:[0,1]
	v_pk_mul_f32 v[70:71], v[70:71], v[174:175] op_sel_hi:[1,0] neg_lo:[0,1] neg_hi:[0,1]
	v_pk_mul_f32 v[72:73], v[72:73], v[174:175] op_sel_hi:[1,0] neg_lo:[0,1] neg_hi:[0,1]
	v_pk_mul_f32 v[66:67], v[66:67], v[174:175] op_sel_hi:[1,0] neg_lo:[0,1] neg_hi:[0,1]
	v_pk_mul_f32 v[68:69], v[68:69], v[174:175] op_sel_hi:[1,0] neg_lo:[0,1] neg_hi:[0,1]
	v_pk_mul_f32 v[62:63], v[62:63], v[174:175] op_sel_hi:[1,0] neg_lo:[0,1] neg_hi:[0,1]
	v_pk_mul_f32 v[64:65], v[64:65], v[174:175] op_sel_hi:[1,0] neg_lo:[0,1] neg_hi:[0,1]
	v_add_f32_e32 v174, v241, v243
	v_sub_f32_e32 v174, v174, v176
	v_pk_fma_f32 v[50:51], v[50:51], v[158:159], v[74:75]
	v_pk_fma_f32 v[52:53], v[52:53], v[160:161], v[76:77]
	v_pk_fma_f32 v[46:47], v[46:47], v[162:163], v[70:71]
	v_pk_fma_f32 v[48:49], v[48:49], v[164:165], v[72:73]
	v_pk_fma_f32 v[42:43], v[42:43], v[166:167], v[66:67]
	v_pk_fma_f32 v[44:45], v[44:45], v[168:169], v[68:69]
	v_pk_fma_f32 v[38:39], v[38:39], v[170:171], v[62:63]
	v_pk_fma_f32 v[40:41], v[40:41], v[172:173], v[64:65]
	v_mov_b32_e32 v62, v175
	v_add_f32_e32 v178, v177, v174
	v_pk_fma_f32 v[158:159], v[62:63], v[30:31], v[50:51] op_sel_hi:[0,1,1]
	v_pk_fma_f32 v[160:161], v[62:63], v[32:33], v[52:53] op_sel_hi:[0,1,1]
	v_pk_fma_f32 v[176:177], v[62:63], v[34:35], v[46:47] op_sel_hi:[0,1,1]
	v_pk_fma_f32 v[244:245], v[62:63], v[36:37], v[48:49] op_sel_hi:[0,1,1]
	v_cvt_pk_bf16_f32 v30, v158, v159
	v_cvt_pk_bf16_f32 v31, v160, v161
	v_cvt_pk_bf16_f32 v32, v176, v177
	v_cvt_pk_bf16_f32 v33, v244, v245
	s_waitcnt lgkmcnt(13)
	v_pk_fma_f32 v[246:247], v[62:63], v[22:23], v[42:43] op_sel_hi:[0,1,1]
	v_pk_fma_f32 v[248:249], v[62:63], v[24:25], v[44:45] op_sel_hi:[0,1,1]
	s_waitcnt lgkmcnt(12)
	v_pk_fma_f32 v[250:251], v[62:63], v[26:27], v[38:39] op_sel_hi:[0,1,1]
	v_pk_fma_f32 v[252:253], v[62:63], v[28:29], v[40:41] op_sel_hi:[0,1,1]
	v_cvt_pk_bf16_f32 v22, v246, v247
	v_cvt_pk_bf16_f32 v23, v248, v249
	v_cvt_pk_bf16_f32 v24, v250, v251
	v_cvt_pk_bf16_f32 v25, v252, v253
	s_waitcnt lgkmcnt(11)
	v_mfma_f32_16x16x32_bf16 v[30:33], v[86:89], v[30:33], 0
	v_add_u32_e32 v174, s19, v216
	v_cndmask_b32_e64 v130, v225, v174, s[14:15]
	v_lshl_add_u32 v130, v130, 2, s3
	s_waitcnt lgkmcnt(10)
	v_mfma_f32_16x16x32_bf16 v[22:25], v[90:93], v[22:25], 0
	ds_read_b128 v[26:29], v229 offset:2080
	ds_read_b128 v[34:37], v229 offset:2096
	ds_read_b128 v[38:41], v229 offset:2208
	ds_read_b128 v[42:45], v229 offset:2224
	ds_write_b32 v130, v178
	ds_read_b128 v[46:49], v230 offset:1568
	ds_read_b128 v[50:53], v230 offset:1632
	ds_read_b32 v231, v239 offset:1568
	ds_read_b64 v[190:191], v8 offset:4672
	v_add_f32_e32 v178, v30, v22
	s_waitcnt lgkmcnt(14)
	v_pk_mul_f32 v[24:25], v[178:179], v[180:181]
	v_add_f32_e32 v22, v31, v23
	s_waitcnt lgkmcnt(12)
	v_pk_mul_f32 v[32:33], v[106:107], v[178:179] op_sel_hi:[1,0] neg_lo:[0,1] neg_hi:[0,1]
	v_pk_mul_f32 v[86:87], v[108:109], v[178:179] op_sel_hi:[1,0] neg_lo:[0,1] neg_hi:[0,1]
	s_waitcnt lgkmcnt(11)
	v_pk_mul_f32 v[88:89], v[102:103], v[178:179] op_sel_hi:[1,0] neg_lo:[0,1] neg_hi:[0,1]
	v_pk_mul_f32 v[90:91], v[104:105], v[178:179] op_sel_hi:[1,0] neg_lo:[0,1] neg_hi:[0,1]
	v_sub_f32_e32 v22, v22, v24
	s_waitcnt lgkmcnt(10)
	v_pk_mul_f32 v[92:93], v[98:99], v[178:179] op_sel_hi:[1,0] neg_lo:[0,1] neg_hi:[0,1]
	v_pk_mul_f32 v[98:99], v[100:101], v[178:179] op_sel_hi:[1,0] neg_lo:[0,1] neg_hi:[0,1]
	s_waitcnt lgkmcnt(9)
	v_pk_mul_f32 v[94:95], v[94:95], v[178:179] op_sel_hi:[1,0] neg_lo:[0,1] neg_hi:[0,1]
	v_pk_mul_f32 v[96:97], v[96:97], v[178:179] op_sel_hi:[1,0] neg_lo:[0,1] neg_hi:[0,1]
	v_add_f32_e32 v175, v25, v22
	v_pk_fma_f32 v[22:23], v[82:83], v[158:159], v[32:33]
	v_pk_fma_f32 v[24:25], v[84:85], v[160:161], v[86:87]
	v_pk_fma_f32 v[30:31], v[78:79], v[176:177], v[88:89]
	v_pk_fma_f32 v[32:33], v[80:81], v[244:245], v[90:91]
	v_mov_b32_e32 v78, v179
	ds_read_b128 v[62:65], v229 offset:3136
	ds_read_b128 v[66:69], v229 offset:3152
	ds_read_b128 v[70:73], v229 offset:3264
	ds_read_b128 v[74:77], v229 offset:3280
	ds_read_b128 v[162:165], v229 offset:3392
	ds_read_b128 v[166:169], v229 offset:3408
	ds_read_b128 v[170:173], v229 offset:3520
	ds_read_b128 v[240:243], v229 offset:3536
	v_pk_fma_f32 v[58:59], v[58:59], v[246:247], v[92:93]
	v_pk_fma_f32 v[60:61], v[60:61], v[248:249], v[98:99]
	v_pk_fma_f32 v[54:55], v[54:55], v[250:251], v[94:95]
	v_pk_fma_f32 v[56:57], v[56:57], v[252:253], v[96:97]
	s_waitcnt lgkmcnt(14)
; __device__ __forceinline__ void scan_phase(LAS unsigned char* lds, const ScanArgs A) {
;     ...
;                 for (int t = 0; t < T; ++t) {
;                     const int tn = (t + 1 < T) ? (t + 1) : t;
;                     bf16x8 nA0, nA1; float nv; f32x2 nc12;
;                     SCAN_LDA(nA0, nA1, nv, nc12, tn);
;                     const f32x4 z4 = (f32x4){0.f, 0.f, 0.f, 0.f};
;                     const f32x4 d0 = __builtin_amdgcn_mfma_f32_16x16x32_bf16(cA0, sb0, z4, 0, 0, 0);
;                     const f32x4 d1 = __builtin_amdgcn_mfma_f32_16x16x32_bf16(cA1, sb1, z4, 0, 0, 0);
;                     f32x4 nw[4], na[4];
;                     SCAN_LDWA(nw, na, tn);
;                     const float sa = -(d0[0] + d1[0]);
;                     const float ov = (d0[1] + d1[1]) + sa * cc12.x + cv * cc12.y;
;                     const f32x2 sa2 = (f32x2){sa, sa}, v2 = (f32x2){cv, cv};
;                     f32x2 tq[2][4];
; #pragma unroll
;                     for (int hh = 0; hh < 2; ++hh) {
;                         tq[hh][0] = sa2 * (f32x2){ca[2 * hh][0], ca[2 * hh][1]}; tq[hh][1] = sa2 * (f32x2){ca[2 * hh][2], ca[2 * hh][3]};
;                         tq[hh][2] = sa2 * (f32x2){ca[2 * hh + 1][0], ca[2 * hh + 1][1]}; tq[hh][3] = sa2 * (f32x2){ca[2 * hh + 1][2], ca[2 * hh + 1][3]}; }
; #pragma unroll
;                     for (int hh = 0; hh < 2; ++hh) {
;                         tq[hh][0] = S[hh][0] * (f32x2){cw[2 * hh][0], cw[2 * hh][1]} + tq[hh][0]; tq[hh][1] = S[hh][1] * (f32x2){cw[2 * hh][2], cw[2 * hh][3]} + tq[hh][1];
;                         tq[hh][2] = S[hh][2] * (f32x2){cw[2 * hh + 1][0], cw[2 * hh + 1][1]} + tq[hh][2]; tq[hh][3] = S[hh][3] * (f32x2){cw[2 * hh + 1][2], cw[2 * hh + 1][3]} + tq[hh][3]; }
; #pragma unroll
;                     for (int hh = 0; hh < 2; ++hh) {
;                         S[hh][0] = v2 * (f32x2){cm[2 * hh][0], cm[2 * hh][1]} + tq[hh][0]; S[hh][1] = v2 * (f32x2){cm[2 * hh][2], cm[2 * hh][3]} + tq[hh][1];
;                         S[hh][2] = v2 * (f32x2){cm[2 * hh + 1][0], cm[2 * hh + 1][1]} + tq[hh][2]; S[hh][3] = v2 * (f32x2){cm[2 * hh + 1][2], cm[2 * hh + 1][3]} + tq[hh][3];
;                         const bf16x8 sbn = __builtin_bit_cast(bf16x8, (u32x4){cvt_pk_bf16(S[hh][0].x, S[hh][0].y), cvt_pk_bf16(S[hh][1].x, S[hh][1].y), cvt_pk_bf16(S[hh][2].x, S[hh][2].y), cvt_pk_bf16(S[hh][3].x, S[hh][3].y)});
	v_pk_fma_f32 v[102:103], v[78:79], v[26:27], v[22:23] op_sel_hi:[0,1,1]
	v_pk_fma_f32 v[104:105], v[78:79], v[28:29], v[24:25] op_sel_hi:[0,1,1]
	v_pk_fma_f32 v[106:107], v[78:79], v[34:35], v[30:31] op_sel_hi:[0,1,1]
	v_pk_fma_f32 v[108:109], v[78:79], v[36:37], v[32:33] op_sel_hi:[0,1,1]
	v_cvt_pk_bf16_f32 v22, v102, v103
	v_cvt_pk_bf16_f32 v23, v104, v105
	v_cvt_pk_bf16_f32 v24, v106, v107
	v_cvt_pk_bf16_f32 v25, v108, v109
	v_pk_fma_f32 v[176:177], v[78:79], v[38:39], v[58:59] op_sel_hi:[0,1,1]
	s_waitcnt lgkmcnt(11)
	v_mfma_f32_16x16x32_bf16 v[46:49], v[46:49], v[22:25], 0
	v_fma_f32 v178, v78, v40, v60
	v_fma_f32 v179, v78, v41, v61
	v_pk_fma_f32 v[180:181], v[78:79], v[42:43], v[54:55] op_sel_hi:[0,1,1]
	v_pk_fma_f32 v[244:245], v[78:79], v[44:45], v[56:57] op_sel_hi:[0,1,1]
	v_cvt_pk_bf16_f32 v26, v176, v177
	v_cvt_pk_bf16_f32 v27, v178, v179
	v_cvt_pk_bf16_f32 v28, v180, v181
	v_cvt_pk_bf16_f32 v29, v244, v245
	s_waitcnt lgkmcnt(10)
	v_mfma_f32_16x16x32_bf16 v[48:51], v[50:53], v[26:29], 0
	ds_read_b128 v[54:57], v229 offset:3648
	ds_read_b128 v[58:61], v229 offset:3664
	ds_read_b128 v[94:97], v229 offset:3776
	ds_read_b128 v[98:101], v229 offset:3792
	ds_write_b32 v130, v175 offset:256
	ds_read_b128 v[38:41], v230 offset:3136
	ds_read_b128 v[42:45], v230 offset:3200
	ds_read_b32 v159, v239 offset:3136
	ds_read_b64 v[160:161], v8 offset:6240
	v_add_f32_e32 v230, v46, v48
	s_waitcnt lgkmcnt(14)
	v_pk_mul_f32 v[50:51], v[230:231], v[190:191]
	v_add_f32_e32 v46, v47, v49
	s_waitcnt lgkmcnt(12)
	v_pk_mul_f32 v[52:53], v[162:163], v[230:231] op_sel_hi:[1,0] neg_lo:[0,1] neg_hi:[0,1]
	v_pk_mul_f32 v[162:163], v[164:165], v[230:231] op_sel_hi:[1,0] neg_lo:[0,1] neg_hi:[0,1]
	s_waitcnt lgkmcnt(11)
	v_pk_mul_f32 v[164:165], v[166:167], v[230:231] op_sel_hi:[1,0] neg_lo:[0,1] neg_hi:[0,1]
	v_pk_mul_f32 v[166:167], v[168:169], v[230:231] op_sel_hi:[1,0] neg_lo:[0,1] neg_hi:[0,1]
	s_waitcnt lgkmcnt(10)
	v_pk_mul_f32 v[168:169], v[170:171], v[230:231] op_sel_hi:[1,0] neg_lo:[0,1] neg_hi:[0,1]
	v_sub_f32_e32 v46, v46, v50
	v_add_f32_e32 v158, v51, v46
	v_pk_fma_f32 v[46:47], v[62:63], v[102:103], v[52:53]
	v_pk_fma_f32 v[62:63], v[70:71], v[176:177], v[168:169]
	v_mov_b32_e32 v70, v231
	v_pk_mul_f32 v[170:171], v[172:173], v[230:231] op_sel_hi:[1,0] neg_lo:[0,1] neg_hi:[0,1]
	s_waitcnt lgkmcnt(9)
	v_pk_mul_f32 v[172:173], v[240:241], v[230:231] op_sel_hi:[1,0] neg_lo:[0,1] neg_hi:[0,1]
	v_pk_mul_f32 v[190:191], v[242:243], v[230:231] op_sel_hi:[1,0] neg_lo:[0,1] neg_hi:[0,1]
	v_pk_fma_f32 v[48:49], v[64:65], v[104:105], v[162:163]
	v_pk_fma_f32 v[50:51], v[66:67], v[106:107], v[164:165]
	v_pk_fma_f32 v[52:53], v[68:69], v[108:109], v[166:167]
	s_waitcnt lgkmcnt(8)
	v_pk_fma_f32 v[162:163], v[70:71], v[54:55], v[46:47] op_sel_hi:[0,1,1]
	s_cmpk_lg_i32 s19, 0x700
	ds_read_b128 v[34:37], v229 offset:4704
	ds_read_b128 v[30:33], v229 offset:4720
	ds_read_b128 v[26:29], v229 offset:4832
	ds_read_b128 v[22:25], v229 offset:4848
	ds_read_b128 v[90:93], v229 offset:4960
	ds_read_b128 v[86:89], v229 offset:4976
	ds_read_b128 v[82:85], v229 offset:5088
	ds_read_b128 v[78:81], v229 offset:5104
	v_pk_fma_f32 v[64:65], v[72:73], v[178:179], v[170:171]
	v_pk_fma_f32 v[66:67], v[74:75], v[180:181], v[172:173]
	v_pk_fma_f32 v[68:69], v[76:77], v[244:245], v[190:191]
	v_pk_fma_f32 v[164:165], v[70:71], v[56:57], v[48:49] op_sel_hi:[0,1,1]
	s_waitcnt lgkmcnt(14)
	v_pk_fma_f32 v[166:167], v[70:71], v[58:59], v[50:51] op_sel_hi:[0,1,1]
	v_pk_fma_f32 v[168:169], v[70:71], v[60:61], v[52:53] op_sel_hi:[0,1,1]
	v_cvt_pk_bf16_f32 v46, v162, v163
	v_cvt_pk_bf16_f32 v47, v164, v165
	v_cvt_pk_bf16_f32 v48, v166, v167
	v_cvt_pk_bf16_f32 v49, v168, v169
	s_cselect_b32 s23, s22, 0x2f78
	s_waitcnt lgkmcnt(11)
; __device__ __forceinline__ void scan_phase(LAS unsigned char* lds, const ScanArgs A) {
;     ...
;                 for (int t = 0; t < T; ++t) {
;                     const int tn = (t + 1 < T) ? (t + 1) : t;
;                     bf16x8 nA0, nA1; float nv; f32x2 nc12;
;                     SCAN_LDA(nA0, nA1, nv, nc12, tn);
;                     const f32x4 z4 = (f32x4){0.f, 0.f, 0.f, 0.f};
;                     const f32x4 d0 = __builtin_amdgcn_mfma_f32_16x16x32_bf16(cA0, sb0, z4, 0, 0, 0);
;                     const f32x4 d1 = __builtin_amdgcn_mfma_f32_16x16x32_bf16(cA1, sb1, z4, 0, 0, 0);
;                     f32x4 nw[4], na[4];
;                     SCAN_LDWA(nw, na, tn);
;                     const float sa = -(d0[0] + d1[0]);
;                     const float ov = (d0[1] + d1[1]) + sa * cc12.x + cv * cc12.y;
;                     const f32x2 sa2 = (f32x2){sa, sa}, v2 = (f32x2){cv, cv};
;                     f32x2 tq[2][4];
; #pragma unroll
;                     for (int hh = 0; hh < 2; ++hh) {
;                         tq[hh][0] = sa2 * (f32x2){ca[2 * hh][0], ca[2 * hh][1]}; tq[hh][1] = sa2 * (f32x2){ca[2 * hh][2], ca[2 * hh][3]};
;                         tq[hh][2] = sa2 * (f32x2){ca[2 * hh + 1][0], ca[2 * hh + 1][1]}; tq[hh][3] = sa2 * (f32x2){ca[2 * hh + 1][2], ca[2 * hh + 1][3]}; }
; #pragma unroll
;                     for (int hh = 0; hh < 2; ++hh) {
;                         tq[hh][0] = S[hh][0] * (f32x2){cw[2 * hh][0], cw[2 * hh][1]} + tq[hh][0]; tq[hh][1] = S[hh][1] * (f32x2){cw[2 * hh][2], cw[2 * hh][3]} + tq[hh][1];
;                         tq[hh][2] = S[hh][2] * (f32x2){cw[2 * hh + 1][0], cw[2 * hh + 1][1]} + tq[hh][2]; tq[hh][3] = S[hh][3] * (f32x2){cw[2 * hh + 1][2], cw[2 * hh + 1][3]} + tq[hh][3]; }
; #pragma unroll
;                     for (int hh = 0; hh < 2; ++hh) {
;                         S[hh][0] = v2 * (f32x2){cm[2 * hh][0], cm[2 * hh][1]} + tq[hh][0]; S[hh][1] = v2 * (f32x2){cm[2 * hh][2], cm[2 * hh][3]} + tq[hh][1];
;                         S[hh][2] = v2 * (f32x2){cm[2 * hh + 1][0], cm[2 * hh + 1][1]} + tq[hh][2]; S[hh][3] = v2 * (f32x2){cm[2 * hh + 1][2], cm[2 * hh + 1][3]} + tq[hh][3];
;                         const bf16x8 sbn = __builtin_bit_cast(bf16x8, (u32x4){cvt_pk_bf16(S[hh][0].x, S[hh][0].y), cvt_pk_bf16(S[hh][1].x, S[hh][1].y), cvt_pk_bf16(S[hh][2].x, S[hh][2].y), cvt_pk_bf16(S[hh][3].x, S[hh][3].y)});
	v_mfma_f32_16x16x32_bf16 v[240:243], v[38:41], v[46:49], 0
	v_fma_f32 v170, v70, v94, v62
	v_fma_f32 v171, v70, v95, v63
	v_pk_fma_f32 v[172:173], v[70:71], v[96:97], v[64:65] op_sel_hi:[0,1,1]
	v_pk_fma_f32 v[178:179], v[70:71], v[98:99], v[66:67] op_sel_hi:[0,1,1]
	v_pk_fma_f32 v[180:181], v[70:71], v[100:101], v[68:69] op_sel_hi:[0,1,1]
	v_cvt_pk_bf16_f32 v50, v170, v171
	v_cvt_pk_bf16_f32 v51, v172, v173
	v_cvt_pk_bf16_f32 v52, v178, v179
	v_cvt_pk_bf16_f32 v53, v180, v181
	s_lshl_b32 s23, s23, 2
	s_waitcnt lgkmcnt(10)
	v_mfma_f32_16x16x32_bf16 v[242:245], v[42:45], v[50:53], 0
	ds_read_b128 v[106:109], v229 offset:5216
	ds_read_b128 v[102:105], v229 offset:5232
	ds_read_b128 v[98:101], v229 offset:5344
	ds_read_b128 v[94:97], v229 offset:5360
	ds_write_b32 v130, v158 offset:512
	v_add_u32_e32 v58, s23, v151
	v_add_u32_e32 v62, s23, v224
	s_add_i32 s56, s2, s23
	ds_read_b128 v[54:57], v58 offset:1024
	ds_read_b128 v[58:61], v58 offset:1088
	ds_read_b32 v175, v62 offset:768
	v_mov_b32_e32 v62, s56
	v_add_u32_e32 v190, s23, v119
	ds_read_b64 v[176:177], v62 offset:1536
	ds_read_b128 v[50:53], v190
	ds_read_b128 v[46:49], v190 offset:16
	ds_read_b128 v[42:45], v190 offset:128
	ds_read_b128 v[38:41], v190 offset:144
	ds_read_b128 v[74:77], v190 offset:256
	ds_read_b128 v[70:73], v190 offset:272
	ds_read_b128 v[66:69], v190 offset:384
	ds_read_b128 v[62:65], v190 offset:400
	v_add_f32_e32 v158, v240, v242
	s_waitcnt lgkmcnt(14)
	v_pk_mul_f32 v[160:161], v[158:159], v[160:161]
	v_pk_mul_f32 v[90:91], v[90:91], v[158:159] op_sel_hi:[1,0] neg_lo:[0,1] neg_hi:[0,1]
	v_pk_mul_f32 v[92:93], v[92:93], v[158:159] op_sel_hi:[1,0] neg_lo:[0,1] neg_hi:[0,1]
	v_pk_mul_f32 v[86:87], v[86:87], v[158:159] op_sel_hi:[1,0] neg_lo:[0,1] neg_hi:[0,1]
	v_pk_mul_f32 v[88:89], v[88:89], v[158:159] op_sel_hi:[1,0] neg_lo:[0,1] neg_hi:[0,1]
	v_pk_mul_f32 v[82:83], v[82:83], v[158:159] op_sel_hi:[1,0] neg_lo:[0,1] neg_hi:[0,1]
	v_pk_mul_f32 v[84:85], v[84:85], v[158:159] op_sel_hi:[1,0] neg_lo:[0,1] neg_hi:[0,1]
	v_pk_mul_f32 v[78:79], v[78:79], v[158:159] op_sel_hi:[1,0] neg_lo:[0,1] neg_hi:[0,1]
	v_pk_mul_f32 v[80:81], v[80:81], v[158:159] op_sel_hi:[1,0] neg_lo:[0,1] neg_hi:[0,1]
	v_add_f32_e32 v158, v241, v243
	v_sub_f32_e32 v158, v158, v160
	v_pk_fma_f32 v[34:35], v[34:35], v[162:163], v[90:91]
	v_pk_fma_f32 v[36:37], v[36:37], v[164:165], v[92:93]
	v_pk_fma_f32 v[30:31], v[30:31], v[166:167], v[86:87]
	v_pk_fma_f32 v[32:33], v[32:33], v[168:169], v[88:89]
	v_pk_fma_f32 v[26:27], v[26:27], v[170:171], v[82:83]
	v_pk_fma_f32 v[28:29], v[28:29], v[172:173], v[84:85]
	v_pk_fma_f32 v[22:23], v[22:23], v[178:179], v[78:79]
	v_pk_fma_f32 v[24:25], v[24:25], v[180:181], v[80:81]
	v_mov_b32_e32 v82, v159
	v_add_f32_e32 v191, v161, v158
	v_pk_fma_f32 v[158:159], v[82:83], v[106:107], v[34:35] op_sel_hi:[0,1,1]
	v_pk_fma_f32 v[160:161], v[82:83], v[108:109], v[36:37] op_sel_hi:[0,1,1]
	v_pk_fma_f32 v[162:163], v[82:83], v[102:103], v[30:31] op_sel_hi:[0,1,1]
	v_pk_fma_f32 v[164:165], v[82:83], v[104:105], v[32:33] op_sel_hi:[0,1,1]
	v_cvt_pk_bf16_f32 v78, v158, v159
	v_cvt_pk_bf16_f32 v79, v160, v161
	v_cvt_pk_bf16_f32 v80, v162, v163
	v_cvt_pk_bf16_f32 v81, v164, v165
	v_pk_fma_f32 v[166:167], v[82:83], v[98:99], v[26:27] op_sel_hi:[0,1,1]
	v_pk_fma_f32 v[168:169], v[82:83], v[100:101], v[28:29] op_sel_hi:[0,1,1]
	s_waitcnt lgkmcnt(13)
	v_pk_fma_f32 v[170:171], v[82:83], v[94:95], v[22:23] op_sel_hi:[0,1,1]
	v_pk_fma_f32 v[172:173], v[82:83], v[96:97], v[24:25] op_sel_hi:[0,1,1]
	v_cvt_pk_bf16_f32 v82, v166, v167
	v_cvt_pk_bf16_f32 v83, v168, v169
	v_cvt_pk_bf16_f32 v84, v170, v171
	v_cvt_pk_bf16_f32 v85, v172, v173
	ds_read_b128 v[30:33], v190 offset:512
	ds_read_b128 v[34:37], v190 offset:528
	ds_read_b128 v[22:25], v190 offset:640
	ds_read_b128 v[26:29], v190 offset:656
	s_addk_i32 s19, 0x100
	s_addk_i32 s22, 0x620
	v_add_u32_e32 v8, 0x1880, v8
	s_cmpk_eq_i32 s19, 0x800
	ds_write_b32 v130, v191 offset:768
	s_cbranch_scc0 .LBB0_1083
